# phase_a adaLN GEMV: 64 weight loads per thread in one burst, loop over batch rows (f32 FMA as before)
# baseline (speedup 1.0000x reference)
.LBB0_49:
	s_or_b64 exec, exec, s[6:7]
	s_mul_hi_i32 s4, s18, 0x2aaaaaab
	s_lshr_b32 s6, s4, 31
	s_ashr_i32 s4, s4, 4
	s_add_i32 s4, s4, s6
	s_mul_i32 s6, s4, 0x60
	s_sub_i32 s6, s18, s6
	s_lshl_b32 s6, s6, 5
	s_ashr_i32 s7, s6, 31
	s_mul_i32 s20, s4, 0xc00000
	s_lshl_b64 s[8:9], s[6:7], 2
	s_mul_hi_i32 s19, s4, 0xc00000
	s_add_u32 s8, s20, s8
	s_addc_u32 s9, s19, s9
	v_lshl_add_u64 v[164:165], v[162:163], 0, s[8:9]
	s_mov_b64 s[8:9], 0x3000
	global_load_dword v64, v[164:165], off
	v_lshl_add_u64 v[164:165], v[164:165], 0, s[8:9]
	global_load_dword v65, v[164:165], off
	v_lshl_add_u64 v[164:165], v[164:165], 0, s[8:9]
	global_load_dword v66, v[164:165], off
	v_lshl_add_u64 v[164:165], v[164:165], 0, s[8:9]
	global_load_dword v67, v[164:165], off
	v_lshl_add_u64 v[164:165], v[164:165], 0, s[8:9]
	global_load_dword v68, v[164:165], off
	v_lshl_add_u64 v[164:165], v[164:165], 0, s[8:9]
	global_load_dword v69, v[164:165], off
	v_lshl_add_u64 v[164:165], v[164:165], 0, s[8:9]
	global_load_dword v70, v[164:165], off
	v_lshl_add_u64 v[164:165], v[164:165], 0, s[8:9]
	global_load_dword v71, v[164:165], off
	v_lshl_add_u64 v[164:165], v[164:165], 0, s[8:9]
	global_load_dword v72, v[164:165], off
	v_lshl_add_u64 v[164:165], v[164:165], 0, s[8:9]
	global_load_dword v73, v[164:165], off
	v_lshl_add_u64 v[164:165], v[164:165], 0, s[8:9]
	global_load_dword v74, v[164:165], off
	v_lshl_add_u64 v[164:165], v[164:165], 0, s[8:9]
	global_load_dword v75, v[164:165], off
	v_lshl_add_u64 v[164:165], v[164:165], 0, s[8:9]
	global_load_dword v76, v[164:165], off
	v_lshl_add_u64 v[164:165], v[164:165], 0, s[8:9]
	global_load_dword v77, v[164:165], off
	v_lshl_add_u64 v[164:165], v[164:165], 0, s[8:9]
	global_load_dword v78, v[164:165], off
	v_lshl_add_u64 v[164:165], v[164:165], 0, s[8:9]
	global_load_dword v79, v[164:165], off
	v_lshl_add_u64 v[164:165], v[164:165], 0, s[8:9]
	global_load_dword v80, v[164:165], off
	v_lshl_add_u64 v[164:165], v[164:165], 0, s[8:9]
	global_load_dword v81, v[164:165], off
	v_lshl_add_u64 v[164:165], v[164:165], 0, s[8:9]
	global_load_dword v82, v[164:165], off
	v_lshl_add_u64 v[164:165], v[164:165], 0, s[8:9]
	global_load_dword v83, v[164:165], off
	v_lshl_add_u64 v[164:165], v[164:165], 0, s[8:9]
	global_load_dword v84, v[164:165], off
	v_lshl_add_u64 v[164:165], v[164:165], 0, s[8:9]
	global_load_dword v85, v[164:165], off
	v_lshl_add_u64 v[164:165], v[164:165], 0, s[8:9]
	global_load_dword v86, v[164:165], off
	v_lshl_add_u64 v[164:165], v[164:165], 0, s[8:9]
	global_load_dword v87, v[164:165], off
	v_lshl_add_u64 v[164:165], v[164:165], 0, s[8:9]
	global_load_dword v88, v[164:165], off
	v_lshl_add_u64 v[164:165], v[164:165], 0, s[8:9]
	global_load_dword v89, v[164:165], off
	v_lshl_add_u64 v[164:165], v[164:165], 0, s[8:9]
	global_load_dword v90, v[164:165], off
	v_lshl_add_u64 v[164:165], v[164:165], 0, s[8:9]
	global_load_dword v91, v[164:165], off
	v_lshl_add_u64 v[164:165], v[164:165], 0, s[8:9]
	global_load_dword v92, v[164:165], off
	v_lshl_add_u64 v[164:165], v[164:165], 0, s[8:9]
	global_load_dword v93, v[164:165], off
	v_lshl_add_u64 v[164:165], v[164:165], 0, s[8:9]
	global_load_dword v94, v[164:165], off
	v_lshl_add_u64 v[164:165], v[164:165], 0, s[8:9]
	global_load_dword v95, v[164:165], off
	v_lshl_add_u64 v[164:165], v[164:165], 0, s[8:9]
	global_load_dword v96, v[164:165], off
	v_lshl_add_u64 v[164:165], v[164:165], 0, s[8:9]
	global_load_dword v97, v[164:165], off
	v_lshl_add_u64 v[164:165], v[164:165], 0, s[8:9]
	global_load_dword v98, v[164:165], off
	v_lshl_add_u64 v[164:165], v[164:165], 0, s[8:9]
	global_load_dword v99, v[164:165], off
	v_lshl_add_u64 v[164:165], v[164:165], 0, s[8:9]
	global_load_dword v100, v[164:165], off
	v_lshl_add_u64 v[164:165], v[164:165], 0, s[8:9]
	global_load_dword v101, v[164:165], off
	v_lshl_add_u64 v[164:165], v[164:165], 0, s[8:9]
	global_load_dword v102, v[164:165], off
	v_lshl_add_u64 v[164:165], v[164:165], 0, s[8:9]
	global_load_dword v103, v[164:165], off
	v_lshl_add_u64 v[164:165], v[164:165], 0, s[8:9]
	global_load_dword v104, v[164:165], off
	v_lshl_add_u64 v[164:165], v[164:165], 0, s[8:9]
	global_load_dword v105, v[164:165], off
	v_lshl_add_u64 v[164:165], v[164:165], 0, s[8:9]
	global_load_dword v106, v[164:165], off
	v_lshl_add_u64 v[164:165], v[164:165], 0, s[8:9]
	global_load_dword v107, v[164:165], off
	v_lshl_add_u64 v[164:165], v[164:165], 0, s[8:9]
	global_load_dword v108, v[164:165], off
	v_lshl_add_u64 v[164:165], v[164:165], 0, s[8:9]
	global_load_dword v109, v[164:165], off
	v_lshl_add_u64 v[164:165], v[164:165], 0, s[8:9]
	global_load_dword v110, v[164:165], off
	v_lshl_add_u64 v[164:165], v[164:165], 0, s[8:9]
	global_load_dword v111, v[164:165], off
	v_lshl_add_u64 v[164:165], v[164:165], 0, s[8:9]
	global_load_dword v112, v[164:165], off
	v_lshl_add_u64 v[164:165], v[164:165], 0, s[8:9]
	global_load_dword v113, v[164:165], off
	v_lshl_add_u64 v[164:165], v[164:165], 0, s[8:9]
	global_load_dword v114, v[164:165], off
	v_lshl_add_u64 v[164:165], v[164:165], 0, s[8:9]
	global_load_dword v115, v[164:165], off
	v_lshl_add_u64 v[164:165], v[164:165], 0, s[8:9]
	global_load_dword v116, v[164:165], off
	v_lshl_add_u64 v[164:165], v[164:165], 0, s[8:9]
	global_load_dword v117, v[164:165], off
	v_lshl_add_u64 v[164:165], v[164:165], 0, s[8:9]
	global_load_dword v118, v[164:165], off
	v_lshl_add_u64 v[164:165], v[164:165], 0, s[8:9]
	global_load_dword v119, v[164:165], off
	v_lshl_add_u64 v[164:165], v[164:165], 0, s[8:9]
	global_load_dword v120, v[164:165], off
	v_lshl_add_u64 v[164:165], v[164:165], 0, s[8:9]
	global_load_dword v121, v[164:165], off
	v_lshl_add_u64 v[164:165], v[164:165], 0, s[8:9]
	global_load_dword v122, v[164:165], off
	v_lshl_add_u64 v[164:165], v[164:165], 0, s[8:9]
	global_load_dword v123, v[164:165], off
	v_lshl_add_u64 v[164:165], v[164:165], 0, s[8:9]
	global_load_dword v124, v[164:165], off
	v_lshl_add_u64 v[164:165], v[164:165], 0, s[8:9]
	global_load_dword v125, v[164:165], off
	v_lshl_add_u64 v[164:165], v[164:165], 0, s[8:9]
	global_load_dword v126, v[164:165], off
	v_lshl_add_u64 v[164:165], v[164:165], 0, s[8:9]
	global_load_dword v127, v[164:165], off
	v_mov_b32_e32 v132, v217
	v_mov_b32_e32 v174, v208
	s_mov_b32 s8, 0
	s_waitcnt lgkmcnt(0)
	s_barrier
	s_waitcnt vmcnt(0)
.Lmod_brow:
	ds_read_b128 v[0:3], v132
	ds_read_b128 v[4:7], v132 offset:16
	ds_read_b128 v[8:11], v132 offset:32
	ds_read_b128 v[12:15], v132 offset:48
	ds_read_b128 v[16:19], v132 offset:64
	ds_read_b128 v[20:23], v132 offset:80
	ds_read_b128 v[24:27], v132 offset:96
	ds_read_b128 v[28:31], v132 offset:112
	ds_read_b128 v[32:35], v132 offset:128
	ds_read_b128 v[36:39], v132 offset:144
	ds_read_b128 v[40:43], v132 offset:160
	ds_read_b128 v[44:47], v132 offset:176
	ds_read_b128 v[48:51], v132 offset:192
	ds_read_b128 v[52:55], v132 offset:208
	ds_read_b128 v[56:59], v132 offset:224
	ds_read_b128 v[60:63], v132 offset:240
	s_waitcnt lgkmcnt(14)
	v_pk_mul_f32 v[166:167], v[0:1], v[64:65]
	v_pk_mul_f32 v[168:169], v[2:3], v[66:67]
	v_pk_mul_f32 v[170:171], v[4:5], v[68:69]
	v_pk_mul_f32 v[172:173], v[6:7], v[70:71]
	s_waitcnt lgkmcnt(12)
	v_pk_fma_f32 v[166:167], v[8:9], v[72:73], v[166:167]
	v_pk_fma_f32 v[168:169], v[10:11], v[74:75], v[168:169]
	v_pk_fma_f32 v[170:171], v[12:13], v[76:77], v[170:171]
	v_pk_fma_f32 v[172:173], v[14:15], v[78:79], v[172:173]
	s_waitcnt lgkmcnt(10)
	v_pk_fma_f32 v[166:167], v[16:17], v[80:81], v[166:167]
	v_pk_fma_f32 v[168:169], v[18:19], v[82:83], v[168:169]
	v_pk_fma_f32 v[170:171], v[20:21], v[84:85], v[170:171]
	v_pk_fma_f32 v[172:173], v[22:23], v[86:87], v[172:173]
	s_waitcnt lgkmcnt(8)
	v_pk_fma_f32 v[166:167], v[24:25], v[88:89], v[166:167]
	v_pk_fma_f32 v[168:169], v[26:27], v[90:91], v[168:169]
	v_pk_fma_f32 v[170:171], v[28:29], v[92:93], v[170:171]
	v_pk_fma_f32 v[172:173], v[30:31], v[94:95], v[172:173]
	s_waitcnt lgkmcnt(6)
	v_pk_fma_f32 v[166:167], v[32:33], v[96:97], v[166:167]
	v_pk_fma_f32 v[168:169], v[34:35], v[98:99], v[168:169]
	v_pk_fma_f32 v[170:171], v[36:37], v[100:101], v[170:171]
	v_pk_fma_f32 v[172:173], v[38:39], v[102:103], v[172:173]
	s_waitcnt lgkmcnt(4)
	v_pk_fma_f32 v[166:167], v[40:41], v[104:105], v[166:167]
	v_pk_fma_f32 v[168:169], v[42:43], v[106:107], v[168:169]
	v_pk_fma_f32 v[170:171], v[44:45], v[108:109], v[170:171]
	v_pk_fma_f32 v[172:173], v[46:47], v[110:111], v[172:173]
	s_waitcnt lgkmcnt(2)
	v_pk_fma_f32 v[166:167], v[48:49], v[112:113], v[166:167]
	v_pk_fma_f32 v[168:169], v[50:51], v[114:115], v[168:169]
	v_pk_fma_f32 v[170:171], v[52:53], v[116:117], v[170:171]
	v_pk_fma_f32 v[172:173], v[54:55], v[118:119], v[172:173]
	s_waitcnt lgkmcnt(0)
	v_pk_fma_f32 v[166:167], v[56:57], v[120:121], v[166:167]
	v_pk_fma_f32 v[168:169], v[58:59], v[122:123], v[168:169]
	v_pk_fma_f32 v[170:171], v[60:61], v[124:125], v[170:171]
	v_pk_fma_f32 v[172:173], v[62:63], v[126:127], v[172:173]
	v_pk_add_f32 v[166:167], v[166:167], v[168:169]
	v_pk_add_f32 v[170:171], v[170:171], v[172:173]
	s_add_i32 s8, s8, 1
	v_pk_add_f32 v[166:167], v[166:167], v[170:171]
	v_add_u32_e32 v132, 0x1000, v132
	s_cmp_lg_u32 s8, 16
	v_add_f32_e32 v166, v166, v167
	ds_write_b32 v174, v166
	v_add_u32_e32 v174, 0x80, v174
	s_cbranch_scc1 .Lmod_brow
	s_mul_i32 s7, s4, 0xc00
	s_add_i32 s7, s7, s6
	v_or_b32_e32 v0, s7, v198
	v_readlane_b32 s72, v254, 9
	v_ashrrev_i32_e32 v1, 31, v0
	v_readlane_b32 s82, v254, 19
	v_readlane_b32 s83, v254, 20
	s_waitcnt lgkmcnt(0)
	s_barrier
	v_lshl_add_u64 v[0:1], v[0:1], 2, s[82:83]
	global_load_dword v18, v[0:1], off
	ds_read2st64_b32 v[0:1], v209 offset1:8
	ds_read2st64_b32 v[2:3], v209 offset0:16 offset1:24
	ds_read2st64_b32 v[4:5], v209 offset0:32 offset1:40
	ds_read2st64_b32 v[6:7], v209 offset0:48 offset1:56
	ds_read2st64_b32 v[8:9], v209 offset0:64 offset1:72
	ds_read2st64_b32 v[10:11], v209 offset0:80 offset1:88
	ds_read2st64_b32 v[12:13], v209 offset0:96 offset1:104
	ds_read2st64_b32 v[14:15], v209 offset0:112 offset1:120
	s_waitcnt lgkmcnt(7)
	v_add_f32_e32 v0, 0, v0
	v_add_f32_e32 v0, v0, v1
	s_waitcnt lgkmcnt(6)
	v_add_f32_e32 v0, v0, v2
	v_add_f32_e32 v0, v0, v3
	s_waitcnt lgkmcnt(5)
	v_add_f32_e32 v0, v0, v4
	v_add_f32_e32 v0, v0, v5
	s_waitcnt lgkmcnt(4)
	v_add_f32_e32 v0, v0, v6
	v_add_f32_e32 v0, v0, v7
	s_waitcnt lgkmcnt(3)
	v_add_f32_e32 v0, v0, v8
	v_add_f32_e32 v0, v0, v9
	s_waitcnt lgkmcnt(2)
	v_add_f32_e32 v0, v0, v10
	v_lshl_add_u32 v16, s4, 4, v197
	v_add_f32_e32 v0, v0, v11
	v_mul_lo_u32 v16, v16, s11
	s_waitcnt lgkmcnt(1)
	v_add_f32_e32 v0, v0, v12
	v_add_u32_e32 v16, s6, v16
	v_add_f32_e32 v0, v0, v13
	v_or_b32_e32 v16, v16, v198
	s_waitcnt lgkmcnt(0)
	v_add_f32_e32 v0, v0, v14
	v_ashrrev_i32_e32 v17, 31, v16
	v_add_f32_e32 v0, v0, v15
	v_lshl_add_u64 v[16:17], v[16:17], 2, s[38:39]
	v_readlane_b32 s73, v254, 10
	v_readlane_b32 s74, v254, 11
	v_readlane_b32 s75, v254, 12
	v_readlane_b32 s76, v254, 13
	v_readlane_b32 s77, v254, 14
	v_readlane_b32 s78, v254, 15
	v_readlane_b32 s79, v254, 16
	v_readlane_b32 s80, v254, 17
	v_readlane_b32 s81, v254, 18
	v_readlane_b32 s84, v254, 21
	v_readlane_b32 s85, v254, 22
	v_readlane_b32 s86, v254, 23
	v_readlane_b32 s87, v254, 24
	s_waitcnt vmcnt(0)
	v_add_f32_e32 v0, v0, v18
	global_store_dword v[16:17], v0, off
	s_barrier
	s_branch .LBB0_23
